# NSA interior tiles: both halves' row-max trees and cross-half bpermutes issued up front (second half's max hides the first bpermute latency)
# speedup vs baseline: 1.0124x; 1.0007x over previous
.LBB0_283:
	s_add_i32 s13, s12, 1
	s_min_i32 s4, s13, s10
	s_lshl_b32 s96, s4, 6
	s_lshl_b64 s[6:7], s[96:97], 7
	s_lshl_b64 s[4:5], s[96:97], 1
	v_lshl_add_u64 v[2:3], v[190:191], 0, s[6:7]
	global_load_dwordx4 v[8:11], v[2:3], off offset:-2048
	s_nop 0
	global_load_dwordx4 v[4:7], v[2:3], off offset:2048
	v_lshl_add_u64 v[2:3], v[162:163], 0, s[4:5]
	v_lshl_add_u64 v[48:49], v[164:165], 0, s[4:5]
	global_load_dwordx4 v[12:15], v[2:3], off
	global_load_dwordx4 v[112:115], v[48:49], off
	s_and_b32 s14, s12, 1
	s_mul_i32 s4, s14, 0x4800
	v_lshrrev_b64 v[2:3], s12, v[128:129]
	s_lshl_b32 s15, s12, 6
	v_and_b32_e32 v0, 1, v2
	s_or_b32 s5, s15, 63
	v_or_b32_e32 v3, s4, v131
	v_cmp_eq_u64_e64 s[38:39], 0, v[0:1]
	s_cmp_gt_i32 s5, s8
	v_add_u32_e32 v172, v3, v161
	s_mov_b64 s[4:5], -1
	s_cbranch_scc1 .LBB0_289
	v_mad_u32_u24 v0, v217, s37, v3
	v_lshl_add_u32 v215, v156, 1, v3
	ds_read_b128 v[220:223], v0
	ds_read_b128 v[236:239], v0 offset:4608
	ds_read_b128 v[224:227], v0 offset:32
	ds_read_b128 v[240:243], v0 offset:4640
	ds_read_b128 v[228:231], v0 offset:64
	ds_read_b128 v[244:247], v0 offset:4672
	ds_read_b128 v[232:235], v0 offset:96
	ds_read_b128 v[248:251], v0 offset:4704
	ds_read_b128 v[64:67], v215 offset:9216
	ds_read_b128 v[68:71], v215 offset:13824
	ds_read_b128 v[72:75], v215 offset:9248
	ds_read_b128 v[76:79], v215 offset:13856
	s_waitcnt lgkmcnt(11)
	v_mfma_f32_32x32x16_bf16 v[80:95], v[220:223], v[96:99], 0
	s_waitcnt lgkmcnt(10)
	v_mfma_f32_32x32x16_bf16 v[48:63], v[236:239], v[96:99], 0
	s_waitcnt lgkmcnt(9)
	v_mfma_f32_32x32x16_bf16 v[80:95], v[224:227], v[100:103], v[80:95]
	s_waitcnt lgkmcnt(8)
	v_mfma_f32_32x32x16_bf16 v[48:63], v[240:243], v[100:103], v[48:63]
	s_waitcnt lgkmcnt(7)
	v_mfma_f32_32x32x16_bf16 v[80:95], v[228:231], v[104:107], v[80:95]
	s_waitcnt lgkmcnt(6)
	v_mfma_f32_32x32x16_bf16 v[48:63], v[244:247], v[104:107], v[48:63]
	s_waitcnt lgkmcnt(5)
	v_mfma_f32_32x32x16_bf16 v[80:95], v[232:235], v[108:111], v[80:95]
	s_waitcnt lgkmcnt(4)
	v_mfma_f32_32x32x16_bf16 v[48:63], v[248:251], v[108:111], v[48:63]
	ds_read_b128 v[220:223], v215 offset:9280
	ds_read_b128 v[224:227], v215 offset:13888
	ds_read_b128 v[228:231], v215 offset:9312
	ds_read_b128 v[232:235], v215 offset:13920
	s_nop 7
	v_max3_f32 v0, v80, v81, v82
	v_max3_f32 v2, v88, v89, v90
	v_max3_f32 v0, v0, v83, v84
	v_max3_f32 v2, v2, v91, v92
	v_max3_f32 v0, v0, v85, v86
	v_max3_f32 v2, v2, v93, v94
	v_max3_f32 v0, v0, v87, v95
	v_max_f32_e32 v0, v0, v2
	v_cndmask_b32_e64 v0, v0, v202, s[38:39]
	ds_bpermute_b32 v2, v119, v0
	v_max3_f32 v175, v48, v49, v50
	v_max3_f32 v214, v56, v57, v58
	v_max3_f32 v175, v175, v51, v52
	v_max3_f32 v214, v214, v59, v60
	v_max3_f32 v175, v175, v53, v54
	v_max3_f32 v214, v214, v61, v62
	v_max3_f32 v175, v175, v55, v63
	v_max_f32_e32 v175, v175, v214
	v_cndmask_b32_e64 v175, v175, v202, s[38:39]
	ds_bpermute_b32 v214, v119, v175
	s_waitcnt lgkmcnt(1)
	v_max3_f32 v173, v167, v0, v2
	v_sub_f32_e32 v0, v167, v173
	v_exp_f32_e32 v0, v0
	v_cmp_eq_f32_e32 vcc, v173, v167
	s_cmp_eq_u64 vcc, exec
	s_cbranch_scc1 .Lnsw_keep0
	v_pk_mul_f32 v[46:47], v[46:47], v[0:1] op_sel_hi:[1,0]
	v_pk_mul_f32 v[44:45], v[44:45], v[0:1] op_sel_hi:[1,0]
	v_pk_mul_f32 v[42:43], v[42:43], v[0:1] op_sel_hi:[1,0]
	v_pk_mul_f32 v[40:41], v[40:41], v[0:1] op_sel_hi:[1,0]
	v_pk_mul_f32 v[38:39], v[38:39], v[0:1] op_sel_hi:[1,0]
	v_pk_mul_f32 v[36:37], v[36:37], v[0:1] op_sel_hi:[1,0]
	v_pk_mul_f32 v[34:35], v[34:35], v[0:1] op_sel_hi:[1,0]
	v_pk_mul_f32 v[32:33], v[32:33], v[0:1] op_sel_hi:[1,0]
	v_pk_mul_f32 v[30:31], v[30:31], v[0:1] op_sel_hi:[1,0]
	v_pk_mul_f32 v[28:29], v[28:29], v[0:1] op_sel_hi:[1,0]
	v_pk_mul_f32 v[26:27], v[26:27], v[0:1] op_sel_hi:[1,0]
	v_pk_mul_f32 v[24:25], v[24:25], v[0:1] op_sel_hi:[1,0]
	v_pk_mul_f32 v[22:23], v[22:23], v[0:1] op_sel_hi:[1,0]
	v_pk_mul_f32 v[20:21], v[20:21], v[0:1] op_sel_hi:[1,0]
	v_pk_mul_f32 v[18:19], v[18:19], v[0:1] op_sel_hi:[1,0]
	v_pk_mul_f32 v[16:17], v[16:17], v[0:1] op_sel_hi:[1,0]
.Lnsw_keep0:
	v_mov_b32_e32 v167, v173
	v_cndmask_b32_e64 v174, v173, v206, s[38:39]
	v_sub_f32_e32 v80, v80, v174
	v_exp_f32_e32 v80, v80
	v_sub_f32_e32 v81, v81, v174
	v_exp_f32_e32 v81, v81
	v_add_f32_e32 v213, 0, v80
	v_sub_f32_e32 v82, v82, v174
	v_exp_f32_e32 v82, v82
	v_add_f32_e32 v213, v81, v213
	v_sub_f32_e32 v83, v83, v174
	v_exp_f32_e32 v83, v83
	v_add_f32_e32 v213, v82, v213
	v_cvt_pk_bf16_f32 v176, v80, v81
	v_sub_f32_e32 v84, v84, v174
	v_exp_f32_e32 v84, v84
	v_add_f32_e32 v213, v83, v213
	v_sub_f32_e32 v85, v85, v174
	v_exp_f32_e32 v85, v85
	v_add_f32_e32 v213, v84, v213
	v_cvt_pk_bf16_f32 v177, v82, v83
	v_sub_f32_e32 v86, v86, v174
	v_exp_f32_e32 v86, v86
	v_add_f32_e32 v213, v85, v213
	v_sub_f32_e32 v87, v87, v174
	v_exp_f32_e32 v87, v87
	v_add_f32_e32 v213, v86, v213
	v_cvt_pk_bf16_f32 v178, v84, v85
	v_sub_f32_e32 v88, v88, v174
	v_exp_f32_e32 v88, v88
	v_add_f32_e32 v213, v87, v213
	v_sub_f32_e32 v89, v89, v174
	v_exp_f32_e32 v89, v89
	v_add_f32_e32 v213, v88, v213
	v_cvt_pk_bf16_f32 v179, v86, v87
	v_sub_f32_e32 v90, v90, v174
	v_exp_f32_e32 v90, v90
	v_add_f32_e32 v213, v89, v213
	v_mfma_f32_32x32x16_bf16 v[32:47], v[64:67], v[176:179], v[32:47]
	v_mfma_f32_32x32x16_bf16 v[16:31], v[68:71], v[176:179], v[16:31]
	v_sub_f32_e32 v91, v91, v174
	v_exp_f32_e32 v91, v91
	v_add_f32_e32 v213, v90, v213
	v_cvt_pk_bf16_f32 v180, v88, v89
	v_sub_f32_e32 v92, v92, v174
	v_exp_f32_e32 v92, v92
	v_add_f32_e32 v213, v91, v213
	v_sub_f32_e32 v93, v93, v174
	v_exp_f32_e32 v93, v93
	v_add_f32_e32 v213, v92, v213
	v_cvt_pk_bf16_f32 v181, v90, v91
	v_sub_f32_e32 v94, v94, v174
	v_exp_f32_e32 v94, v94
	v_add_f32_e32 v213, v93, v213
	v_sub_f32_e32 v95, v95, v174
	v_exp_f32_e32 v95, v95
	v_add_f32_e32 v213, v94, v213
	v_cvt_pk_bf16_f32 v182, v92, v93
	v_add_f32_e32 v213, v95, v213
	v_cvt_pk_bf16_f32 v183, v94, v95
	v_fmac_f32_e32 v213, v169, v0
	v_mov_b32_e32 v169, v213
	s_nop 0
	v_mfma_f32_32x32x16_bf16 v[32:47], v[72:75], v[180:183], v[32:47]
	v_mfma_f32_32x32x16_bf16 v[16:31], v[76:79], v[180:183], v[16:31]
	s_waitcnt lgkmcnt(0)
	v_max3_f32 v173, v167, v175, v214
	v_sub_f32_e32 v0, v167, v173
	v_exp_f32_e32 v0, v0
	v_cmp_eq_f32_e32 vcc, v173, v167
	s_cmp_eq_u64 vcc, exec
	s_cbranch_scc1 .Lnsw_keep1
	v_pk_mul_f32 v[46:47], v[46:47], v[0:1] op_sel_hi:[1,0]
	v_pk_mul_f32 v[44:45], v[44:45], v[0:1] op_sel_hi:[1,0]
	v_pk_mul_f32 v[42:43], v[42:43], v[0:1] op_sel_hi:[1,0]
	v_pk_mul_f32 v[40:41], v[40:41], v[0:1] op_sel_hi:[1,0]
	v_pk_mul_f32 v[38:39], v[38:39], v[0:1] op_sel_hi:[1,0]
	v_pk_mul_f32 v[36:37], v[36:37], v[0:1] op_sel_hi:[1,0]
	v_pk_mul_f32 v[34:35], v[34:35], v[0:1] op_sel_hi:[1,0]
	v_pk_mul_f32 v[32:33], v[32:33], v[0:1] op_sel_hi:[1,0]
	v_pk_mul_f32 v[30:31], v[30:31], v[0:1] op_sel_hi:[1,0]
	v_pk_mul_f32 v[28:29], v[28:29], v[0:1] op_sel_hi:[1,0]
	v_pk_mul_f32 v[26:27], v[26:27], v[0:1] op_sel_hi:[1,0]
	v_pk_mul_f32 v[24:25], v[24:25], v[0:1] op_sel_hi:[1,0]
	v_pk_mul_f32 v[22:23], v[22:23], v[0:1] op_sel_hi:[1,0]
	v_pk_mul_f32 v[20:21], v[20:21], v[0:1] op_sel_hi:[1,0]
	v_pk_mul_f32 v[18:19], v[18:19], v[0:1] op_sel_hi:[1,0]
	v_pk_mul_f32 v[16:17], v[16:17], v[0:1] op_sel_hi:[1,0]

.LBB0_307:
	s_and_b64 vcc, exec, s[4:5]
	s_cbranch_vccz .Lnsw1_edgeback
	v_mad_u32_u24 v0, v218, s37, v14
	v_lshl_add_u32 v215, v159, 1, v14
	ds_read_b128 v[220:223], v0
	ds_read_b128 v[236:239], v0 offset:4608
	ds_read_b128 v[224:227], v0 offset:32
	ds_read_b128 v[240:243], v0 offset:4640
	ds_read_b128 v[228:231], v0 offset:64
	ds_read_b128 v[244:247], v0 offset:4672
	ds_read_b128 v[232:235], v0 offset:96
	ds_read_b128 v[248:251], v0 offset:4704
	ds_read_b128 v[64:67], v215 offset:9216
	ds_read_b128 v[68:71], v215 offset:13824
	ds_read_b128 v[72:75], v215 offset:9248
	ds_read_b128 v[76:79], v215 offset:13856
	s_waitcnt lgkmcnt(11)
	v_mfma_f32_32x32x16_bf16 v[80:95], v[220:223], v[96:99], 0
	s_waitcnt lgkmcnt(10)
	v_mfma_f32_32x32x16_bf16 v[48:63], v[236:239], v[96:99], 0
	s_waitcnt lgkmcnt(9)
	v_mfma_f32_32x32x16_bf16 v[80:95], v[224:227], v[100:103], v[80:95]
	s_waitcnt lgkmcnt(8)
	v_mfma_f32_32x32x16_bf16 v[48:63], v[240:243], v[100:103], v[48:63]
	s_waitcnt lgkmcnt(7)
	v_mfma_f32_32x32x16_bf16 v[80:95], v[228:231], v[104:107], v[80:95]
	s_waitcnt lgkmcnt(6)
	v_mfma_f32_32x32x16_bf16 v[48:63], v[244:247], v[104:107], v[48:63]
	s_waitcnt lgkmcnt(5)
	v_mfma_f32_32x32x16_bf16 v[80:95], v[232:235], v[108:111], v[80:95]
	s_waitcnt lgkmcnt(4)
	v_mfma_f32_32x32x16_bf16 v[48:63], v[248:251], v[108:111], v[48:63]
	ds_read_b128 v[220:223], v215 offset:9280
	ds_read_b128 v[224:227], v215 offset:13888
	ds_read_b128 v[228:231], v215 offset:9312
	ds_read_b128 v[232:235], v215 offset:13920
	s_nop 7
	v_max3_f32 v0, v80, v81, v82
	v_max3_f32 v216, v88, v89, v90
	v_max3_f32 v0, v0, v83, v84
	v_max3_f32 v216, v216, v91, v92
	v_max3_f32 v0, v0, v85, v86
	v_max3_f32 v216, v216, v93, v94
	v_max3_f32 v0, v0, v87, v95
	v_max_f32_e32 v0, v0, v216
	ds_bpermute_b32 v216, v119, v0
	v_max3_f32 v175, v48, v49, v50
	v_max3_f32 v214, v56, v57, v58
	v_max3_f32 v175, v175, v51, v52
	v_max3_f32 v214, v214, v59, v60
	v_max3_f32 v175, v175, v53, v54
	v_max3_f32 v214, v214, v61, v62
	v_max3_f32 v175, v175, v55, v63
	v_max_f32_e32 v175, v175, v214
	ds_bpermute_b32 v214, v119, v175
	s_waitcnt lgkmcnt(1)
	v_max3_f32 v173, v168, v0, v216
	v_sub_f32_e32 v0, v168, v173
	v_exp_f32_e32 v0, v0
	v_cmp_eq_f32_e32 vcc, v173, v168
	s_cmp_eq_u64 vcc, exec
	s_cbranch_scc1 .Lnsw1_keep0
	v_pk_mul_f32 v[46:47], v[46:47], v[0:1] op_sel_hi:[1,0]
	v_pk_mul_f32 v[44:45], v[44:45], v[0:1] op_sel_hi:[1,0]
	v_pk_mul_f32 v[42:43], v[42:43], v[0:1] op_sel_hi:[1,0]
	v_pk_mul_f32 v[40:41], v[40:41], v[0:1] op_sel_hi:[1,0]
	v_pk_mul_f32 v[38:39], v[38:39], v[0:1] op_sel_hi:[1,0]
	v_pk_mul_f32 v[36:37], v[36:37], v[0:1] op_sel_hi:[1,0]
	v_pk_mul_f32 v[34:35], v[34:35], v[0:1] op_sel_hi:[1,0]
	v_pk_mul_f32 v[32:33], v[32:33], v[0:1] op_sel_hi:[1,0]
	v_pk_mul_f32 v[30:31], v[30:31], v[0:1] op_sel_hi:[1,0]
	v_pk_mul_f32 v[28:29], v[28:29], v[0:1] op_sel_hi:[1,0]
	v_pk_mul_f32 v[26:27], v[26:27], v[0:1] op_sel_hi:[1,0]
	v_pk_mul_f32 v[24:25], v[24:25], v[0:1] op_sel_hi:[1,0]
	v_pk_mul_f32 v[22:23], v[22:23], v[0:1] op_sel_hi:[1,0]
	v_pk_mul_f32 v[20:21], v[20:21], v[0:1] op_sel_hi:[1,0]
	v_pk_mul_f32 v[18:19], v[18:19], v[0:1] op_sel_hi:[1,0]
	v_pk_mul_f32 v[16:17], v[16:17], v[0:1] op_sel_hi:[1,0]
.Lnsw1_keep0:
	v_mov_b32_e32 v168, v173
	v_mov_b32_e32 v174, v173
	v_sub_f32_e32 v80, v80, v174
	v_exp_f32_e32 v80, v80
	v_sub_f32_e32 v81, v81, v174
	v_exp_f32_e32 v81, v81
	v_add_f32_e32 v213, 0, v80
	v_sub_f32_e32 v82, v82, v174
	v_exp_f32_e32 v82, v82
	v_add_f32_e32 v213, v81, v213
	v_sub_f32_e32 v83, v83, v174
	v_exp_f32_e32 v83, v83
	v_add_f32_e32 v213, v82, v213
	v_cvt_pk_bf16_f32 v176, v80, v81
	v_sub_f32_e32 v84, v84, v174
	v_exp_f32_e32 v84, v84
	v_add_f32_e32 v213, v83, v213
	v_sub_f32_e32 v85, v85, v174
	v_exp_f32_e32 v85, v85
	v_add_f32_e32 v213, v84, v213
	v_cvt_pk_bf16_f32 v177, v82, v83
	v_sub_f32_e32 v86, v86, v174
	v_exp_f32_e32 v86, v86
	v_add_f32_e32 v213, v85, v213
	v_sub_f32_e32 v87, v87, v174
	v_exp_f32_e32 v87, v87
	v_add_f32_e32 v213, v86, v213
	v_cvt_pk_bf16_f32 v178, v84, v85
	v_sub_f32_e32 v88, v88, v174
	v_exp_f32_e32 v88, v88
	v_add_f32_e32 v213, v87, v213
	v_sub_f32_e32 v89, v89, v174
	v_exp_f32_e32 v89, v89
	v_add_f32_e32 v213, v88, v213
	v_cvt_pk_bf16_f32 v179, v86, v87
	v_sub_f32_e32 v90, v90, v174
	v_exp_f32_e32 v90, v90
	v_add_f32_e32 v213, v89, v213
	v_mfma_f32_32x32x16_bf16 v[32:47], v[64:67], v[176:179], v[32:47]
	v_mfma_f32_32x32x16_bf16 v[16:31], v[68:71], v[176:179], v[16:31]
	v_sub_f32_e32 v91, v91, v174
	v_exp_f32_e32 v91, v91
	v_add_f32_e32 v213, v90, v213
	v_cvt_pk_bf16_f32 v180, v88, v89
	v_sub_f32_e32 v92, v92, v174
	v_exp_f32_e32 v92, v92
	v_add_f32_e32 v213, v91, v213
	v_sub_f32_e32 v93, v93, v174
	v_exp_f32_e32 v93, v93
	v_add_f32_e32 v213, v92, v213
	v_cvt_pk_bf16_f32 v181, v90, v91
	v_sub_f32_e32 v94, v94, v174
	v_exp_f32_e32 v94, v94
	v_add_f32_e32 v213, v93, v213
	v_sub_f32_e32 v95, v95, v174
	v_exp_f32_e32 v95, v95
	v_add_f32_e32 v213, v94, v213
	v_cvt_pk_bf16_f32 v182, v92, v93
	v_add_f32_e32 v213, v95, v213
	v_cvt_pk_bf16_f32 v183, v94, v95
	v_fmac_f32_e32 v213, v169, v0
	v_mov_b32_e32 v169, v213
	s_nop 0
	v_mfma_f32_32x32x16_bf16 v[32:47], v[72:75], v[180:183], v[32:47]
	v_mfma_f32_32x32x16_bf16 v[16:31], v[76:79], v[180:183], v[16:31]
	s_waitcnt lgkmcnt(0)
	v_max3_f32 v173, v168, v175, v214
	v_sub_f32_e32 v0, v168, v173
	v_exp_f32_e32 v0, v0
	v_cmp_eq_f32_e32 vcc, v173, v168
	s_cmp_eq_u64 vcc, exec
	s_cbranch_scc1 .Lnsw1_keep1
	v_pk_mul_f32 v[46:47], v[46:47], v[0:1] op_sel_hi:[1,0]
	v_pk_mul_f32 v[44:45], v[44:45], v[0:1] op_sel_hi:[1,0]
	v_pk_mul_f32 v[42:43], v[42:43], v[0:1] op_sel_hi:[1,0]
	v_pk_mul_f32 v[40:41], v[40:41], v[0:1] op_sel_hi:[1,0]
	v_pk_mul_f32 v[38:39], v[38:39], v[0:1] op_sel_hi:[1,0]
	v_pk_mul_f32 v[36:37], v[36:37], v[0:1] op_sel_hi:[1,0]
	v_pk_mul_f32 v[34:35], v[34:35], v[0:1] op_sel_hi:[1,0]
	v_pk_mul_f32 v[32:33], v[32:33], v[0:1] op_sel_hi:[1,0]
	v_pk_mul_f32 v[30:31], v[30:31], v[0:1] op_sel_hi:[1,0]
	v_pk_mul_f32 v[28:29], v[28:29], v[0:1] op_sel_hi:[1,0]
	v_pk_mul_f32 v[26:27], v[26:27], v[0:1] op_sel_hi:[1,0]
	v_pk_mul_f32 v[24:25], v[24:25], v[0:1] op_sel_hi:[1,0]
	v_pk_mul_f32 v[22:23], v[22:23], v[0:1] op_sel_hi:[1,0]
	v_pk_mul_f32 v[20:21], v[20:21], v[0:1] op_sel_hi:[1,0]
	v_pk_mul_f32 v[18:19], v[18:19], v[0:1] op_sel_hi:[1,0]
	v_pk_mul_f32 v[16:17], v[16:17], v[0:1] op_sel_hi:[1,0]
